# retention unit start: vmcnt(0) replaced by a per-unit counted wait (first unit vmcnt(4): tile 1's K pieces stay in flight; second unit vmcnt(8): the previous unit's eight epilogue stores stay in fligh
# baseline (speedup 1.0000x reference)
; #define RT_BAR() do { asm volatile("s_waitcnt lgkmcnt(0)" ::: "memory"); __builtin_amdgcn_s_barrier(); asm volatile("" ::: "memory"); } while (0)
; __device__ __forceinline__ void p2_ret(const Frame& F, ArgsP a, int layer) {
;     ...
;         for (int uu = 0; uu < 2; ++uu) {
;             const int qi = uu ? p : 15 - p, ntile = 2 * (qi + 1);
;             const size_t tokq = (size_t)b * SEQ + qi * 128;
;             f32x16 oacc[4];
; #pragma unroll
;             for (int db = 0; db < 4; ++db)
; #pragma unroll
;                 for (int r = 0; r < 16; ++r) oacc[db][r] = 0.f;
;             asm volatile("s_waitcnt vmcnt(0)" ::: "memory"); RT_BAR();
.LBB0_355:
	s_xor_b64 s[72:73], s[74:75], -1
	s_and_b64 s[2:3], s[74:75], exec
	s_cbranch_scc1 .Lus_first
	s_waitcnt vmcnt(8)
	s_branch .Lus_done

; #define RT_BAR() do { asm volatile("s_waitcnt lgkmcnt(0)" ::: "memory"); __builtin_amdgcn_s_barrier(); asm volatile("" ::: "memory"); } while (0)
; __device__ __forceinline__ void p2_ret(const Frame& F, ArgsP a, int layer) {
;     ...
;             const int qi = uu ? p : 15 - p, ntile = 2 * (qi + 1);
;             const size_t tokq = (size_t)b * SEQ + qi * 128;
;             f32x16 oacc[4];
; #pragma unroll
;             for (int db = 0; db < 4; ++db)
; #pragma unroll
;                 for (int r = 0; r < 16; ++r) oacc[db][r] = 0.f;
;             asm volatile("s_waitcnt vmcnt(0)" ::: "memory"); RT_BAR();
.Lus_done:
	s_cselect_b32 s96, s89, s50
	s_waitcnt lgkmcnt(0)
	s_barrier
	s_lshl_b32 s19, s96, 7
	s_lshl_b32 s11, s96, 8
	v_mov_b32_e32 v34, 0
	s_lshl_b32 s29, s96, 1
	s_add_i32 s97, s81, s19
	s_bitset1_b32 s11, 7
	s_mov_b32 s31, 0
	s_mov_b32 s27, s88
	s_mov_b32 s30, 0
	s_mov_b32 s91, 0
	v_mov_b32_e32 v35, v34
	v_mov_b32_e32 v36, v34
	v_mov_b32_e32 v37, v34
	v_mov_b32_e32 v38, v34
	v_mov_b32_e32 v39, v34
	v_mov_b32_e32 v40, v34
	v_mov_b32_e32 v41, v34
	v_mov_b32_e32 v42, v34
	v_mov_b32_e32 v43, v34
	v_mov_b32_e32 v44, v34
	v_mov_b32_e32 v45, v34
	v_mov_b32_e32 v46, v34
	v_mov_b32_e32 v47, v34
	v_mov_b32_e32 v48, v34
	v_mov_b32_e32 v49, v34
	v_mov_b32_e32 v50, v34
	v_mov_b32_e32 v51, v34
	v_mov_b32_e32 v52, v34
	v_mov_b32_e32 v53, v34
	v_mov_b32_e32 v54, v34
	v_mov_b32_e32 v55, v34
	v_mov_b32_e32 v56, v34
	v_mov_b32_e32 v57, v34
	v_mov_b32_e32 v58, v34
	v_mov_b32_e32 v59, v34
	v_mov_b32_e32 v60, v34
	v_mov_b32_e32 v61, v34
	v_mov_b32_e32 v62, v34
	v_mov_b32_e32 v63, v34
	v_mov_b32_e32 v64, v34
	v_mov_b32_e32 v65, v34
	v_mov_b32_e32 v66, v34
	v_mov_b32_e32 v67, v34
	v_mov_b32_e32 v68, v34
	v_mov_b32_e32 v69, v34
	v_mov_b32_e32 v70, v34
	v_mov_b32_e32 v71, v34
	v_mov_b32_e32 v72, v34
	v_mov_b32_e32 v73, v34
	v_mov_b32_e32 v74, v34
	v_mov_b32_e32 v75, v34
	v_mov_b32_e32 v76, v34
	v_mov_b32_e32 v77, v34
	v_mov_b32_e32 v78, v34
	v_mov_b32_e32 v79, v34
	v_mov_b32_e32 v80, v34
	v_mov_b32_e32 v81, v34
	v_mov_b32_e32 v82, v34
	v_mov_b32_e32 v83, v34
	v_mov_b32_e32 v84, v34
	v_mov_b32_e32 v85, v34
	v_mov_b32_e32 v86, v34
	v_mov_b32_e32 v87, v34
	v_mov_b32_e32 v88, v34
	v_mov_b32_e32 v89, v34
	v_mov_b32_e32 v90, v34
	v_mov_b32_e32 v91, v34
	v_mov_b32_e32 v92, v34
	v_mov_b32_e32 v93, v34
	v_mov_b32_e32 v94, v34
	v_mov_b32_e32 v95, v34
	v_mov_b32_e32 v96, v34
	v_mov_b32_e32 v97, v34
	s_branch .LBB0_358
